# also nt: the read-once conv input (zch) loads
# speedup vs baseline: 1.0115x; 1.0054x over previous
.LBB0_411:
	v_max_i32_e32 v2, 2, v80
	v_add_u32_e32 v0, -2, v2
	v_mov_b32_e32 v1, v195
	v_lshlrev_b64 v[0:1], 11, v[0:1]
	v_lshl_add_u64 v[0:1], v[128:129], 0, v[0:1]
	global_load_dwordx4 v[24:27], v[0:1], off
	v_mov_b32_e32 v1, v195
	v_add_u32_e32 v0, -1, v2
	v_lshlrev_b64 v[0:1], 11, v[0:1]
	v_lshl_add_u64 v[0:1], v[128:129], 0, v[0:1]
	global_load_dwordx4 v[28:31], v[0:1], off
	v_add_u32_e32 v0, 0xffffc000, v80
	s_movk_i32 s0, 0x4000
	v_lshrrev_b32_e32 v194, 5, v0
	v_cmp_gt_i32_e32 vcc, s0, v80
	v_lshlrev_b64 v[0:1], 11, v[194:195]
	v_and_b32_e32 v3, 0x7f0, v80
	v_cndmask_b32_e64 v1, v1, 0, vcc
	v_cndmask_b32_e64 v0, v0, 0, vcc
	v_lshl_add_u64 v[0:1], v[0:1], 2, v[130:131]
	global_load_dwordx4 v[32:35], v[0:1], off
	global_load_dwordx4 v[36:39], v[0:1], off offset:16
	s_movk_i32 s0, 0x1000
	v_cndmask_b32_e32 v104, v158, v3, vcc
	v_lshl_add_u64 v[2:3], v[0:1], 0, s[24:25]
	v_add_co_u32_e64 v0, s[0:1], s0, v0
	v_ashrrev_i32_e32 v81, 31, v80
	s_nop 0
	v_addc_co_u32_e64 v1, s[0:1], 0, v1, s[0:1]
	global_load_dwordx4 v[40:43], v[0:1], off
	global_load_dwordx4 v[44:47], v[2:3], off offset:16
	s_nop 0
	global_load_dwordx4 v[0:3], v[122:123], off offset:16
	global_load_dwordx4 v[12:15], v[122:123], off
	global_load_dwordx4 v[4:7], v[124:125], off offset:16
	global_load_dwordx4 v[16:19], v[124:125], off
	global_load_dwordx4 v[8:11], v[126:127], off offset:16
	global_load_dwordx4 v[20:23], v[126:127], off
	v_lshlrev_b32_e32 v105, 1, v120
	s_waitcnt vmcnt(12)
	v_lshlrev_b64 v[100:101], 11, v[80:81]
	v_or_b32_e32 v48, v100, v105
	v_mov_b32_e32 v49, v101
	v_lshl_add_u64 v[50:51], s[74:75], 0, v[48:49]
	v_lshl_add_u64 v[48:49], s[76:77], 0, v[48:49]
	global_load_dwordx4 v[56:59], v[50:51], off
	global_load_dwordx4 v[106:109], v[48:49], off
	v_cmp_eq_u32_e64 s[0:1], 0, v104
	v_lshl_add_u64 v[100:101], v[132:133], 0, v[100:101]
	s_waitcnt vmcnt(13)
	v_and_b32_e32 v48, 0xffff0000, v24
	v_lshlrev_b32_e32 v24, 16, v24
	v_lshlrev_b32_e32 v49, 16, v25
	v_and_b32_e32 v25, 0xffff0000, v25
	v_lshlrev_b32_e32 v50, 16, v26
	s_waitcnt vmcnt(12)
	v_lshlrev_b32_e32 v52, 16, v28
	v_lshlrev_b32_e32 v53, 16, v29
	v_and_b32_e32 v29, 0xffff0000, v29
	v_lshlrev_b32_e32 v55, 16, v31
	v_and_b32_e32 v31, 0xffff0000, v31
	v_and_b32_e32 v26, 0xffff0000, v26
	v_lshlrev_b32_e32 v51, 16, v27
	v_and_b32_e32 v27, 0xffff0000, v27
	v_and_b32_e32 v28, 0xffff0000, v28
	s_waitcnt vmcnt(11)
	v_cndmask_b32_e64 v32, v32, 0, vcc
	v_cndmask_b32_e64 v114, v24, v32, s[0:1]
	v_cndmask_b32_e64 v35, v35, 0, vcc
	s_waitcnt vmcnt(9)
	v_cndmask_b32_e64 v24, v40, 0, vcc
	v_cndmask_b32_e64 v81, v52, v24, s[0:1]
	v_cndmask_b32_e64 v24, v43, 0, vcc
	v_cndmask_b32_e64 v174, v29, v24, s[0:1]
	s_waitcnt vmcnt(8)
	v_cndmask_b32_e64 v24, v47, 0, vcc
	v_cndmask_b32_e64 v175, v31, v24, s[0:1]
	v_add_u32_e32 v24, 1, v80
	v_cndmask_b32_e64 v98, v25, v35, s[0:1]
	v_ashrrev_i32_e32 v25, 31, v24
	v_cndmask_b32_e64 v37, v37, 0, vcc
	v_lshlrev_b64 v[94:95], 11, v[24:25]
	v_cndmask_b32_e64 v39, v39, 0, vcc
	v_cndmask_b32_e64 v154, v26, v37, s[0:1]
	v_cndmask_b32_e64 v26, v41, 0, vcc
	v_or_b32_e32 v24, v94, v105
	v_mov_b32_e32 v25, v95
	v_cndmask_b32_e64 v99, v28, v26, s[0:1]
	v_cndmask_b32_e64 v96, v27, v39, s[0:1]
	v_lshl_add_u64 v[26:27], s[74:75], 0, v[24:25]
	v_lshl_add_u64 v[24:25], s[76:77], 0, v[24:25]
	global_load_dwordx4 v[76:79], v[26:27], off nt
	global_load_dwordx4 v[110:113], v[24:25], off
	v_add_u32_e32 v24, 2, v80
	v_ashrrev_i32_e32 v25, 31, v24
	v_lshlrev_b64 v[92:93], 11, v[24:25]
	v_or_b32_e32 v24, v92, v105
	v_mov_b32_e32 v25, v93
	v_lshl_add_u64 v[26:27], s[74:75], 0, v[24:25]
	v_lshl_add_u64 v[24:25], s[76:77], 0, v[24:25]
	global_load_dwordx4 v[72:75], v[26:27], off nt
	global_load_dwordx4 v[68:71], v[24:25], off
	v_add_u32_e32 v24, 3, v80
	v_ashrrev_i32_e32 v25, 31, v24
	v_lshlrev_b64 v[90:91], 11, v[24:25]
	v_or_b32_e32 v24, v90, v105
	v_mov_b32_e32 v25, v91
	v_lshl_add_u64 v[26:27], s[74:75], 0, v[24:25]
	v_lshl_add_u64 v[24:25], s[76:77], 0, v[24:25]
	global_load_dwordx4 v[64:67], v[26:27], off nt
	global_load_dwordx4 v[60:63], v[24:25], off
	s_waitcnt vmcnt(6)
	v_lshlrev_b32_e32 v117, 16, v106
	v_and_b32_e32 v155, 0xffff0000, v106
	v_lshlrev_b32_e32 v176, 16, v107
	v_and_b32_e32 v177, 0xffff0000, v107
	v_mov_b32_e32 v106, v12
	v_mov_b32_e32 v107, v20
	v_add_u32_e32 v24, 4, v80
	v_ashrrev_i32_e32 v25, 31, v24
	v_cndmask_b32_e64 v36, v36, 0, vcc
	v_lshlrev_b64 v[88:89], 11, v[24:25]
	v_lshlrev_b32_e32 v54, 16, v30
	v_cndmask_b32_e64 v34, v34, 0, vcc
	v_cndmask_b32_e64 v116, v50, v36, s[0:1]
	v_cndmask_b32_e64 v32, v44, 0, vcc
	v_or_b32_e32 v24, v88, v105
	v_mov_b32_e32 v25, v89
	v_lshlrev_b32_e32 v119, 16, v108
	v_and_b32_e32 v157, 0xffff0000, v108
	v_lshlrev_b32_e32 v178, 16, v109
	v_and_b32_e32 v179, 0xffff0000, v109
	v_mov_b32_e32 v108, v0
	v_mov_b32_e32 v109, v8
	v_cndmask_b32_e64 v33, v33, 0, vcc
	v_cndmask_b32_e64 v38, v38, 0, vcc
	v_cndmask_b32_e64 v156, v49, v34, s[0:1]
	v_cndmask_b32_e64 v34, v42, 0, vcc
	v_cndmask_b32_e64 v36, v46, 0, vcc
	v_cndmask_b32_e64 v97, v54, v32, s[0:1]
	v_lshl_add_u64 v[26:27], s[74:75], 0, v[24:25]
	v_cndmask_b32_e64 v118, v48, v33, s[0:1]
	v_cndmask_b32_e64 v102, v51, v38, s[0:1]
	v_cndmask_b32_e64 v172, v53, v34, s[0:1]
	v_cndmask_b32_e64 v173, v55, v36, s[0:1]
	v_lshl_add_u64 v[24:25], s[76:77], 0, v[24:25]
	global_load_dwordx4 v[52:55], v[26:27], off nt
	global_load_dwordx4 v[48:51], v[24:25], off
	v_mov_b32_e32 v160, v13
	v_mov_b32_e32 v161, v21
	v_add_u32_e32 v24, 5, v80
	v_ashrrev_i32_e32 v25, 31, v24
	v_lshlrev_b64 v[86:87], 11, v[24:25]
	v_and_b32_e32 v30, 0xffff0000, v30
	v_cndmask_b32_e64 v33, v45, 0, vcc
	v_or_b32_e32 v24, v86, v105
	v_mov_b32_e32 v25, v87
	v_mov_b32_e32 v162, v1
	v_mov_b32_e32 v163, v9
	v_cndmask_b32_e64 v103, v30, v33, s[0:1]
	v_lshl_add_u64 v[26:27], s[74:75], 0, v[24:25]
	v_lshl_add_u64 v[24:25], s[76:77], 0, v[24:25]
	global_load_dwordx4 v[44:47], v[26:27], off nt
	global_load_dwordx4 v[40:43], v[24:25], off
	v_mov_b32_e32 v164, v14
	v_mov_b32_e32 v165, v22
	v_add_u32_e32 v24, 6, v80
	v_ashrrev_i32_e32 v25, 31, v24
	v_lshlrev_b64 v[84:85], 11, v[24:25]
	v_or_b32_e32 v24, v84, v105
	v_mov_b32_e32 v25, v85
	v_mov_b32_e32 v166, v2
	v_mov_b32_e32 v167, v10
	v_lshl_add_u64 v[26:27], s[74:75], 0, v[24:25]
	v_lshl_add_u64 v[24:25], s[76:77], 0, v[24:25]
	global_load_dwordx4 v[36:39], v[26:27], off nt
	global_load_dwordx4 v[32:35], v[24:25], off
	v_add_u32_e32 v24, 7, v80
	s_waitcnt vmcnt(10)
	v_lshlrev_b32_e32 v180, 16, v110
	v_and_b32_e32 v181, 0xffff0000, v110
	v_lshlrev_b32_e32 v110, 16, v56
	v_mov_b32_e32 v115, v110
	v_pk_mul_f32 v[106:107], v[106:107], v[114:115]
	v_lshlrev_b32_e32 v182, 16, v111
	v_fma_f32 v106, v16, v81, v106
	v_add_f32_e32 v106, v106, v107
	v_and_b32_e32 v183, 0xffff0000, v111
	v_lshlrev_b32_e32 v111, 16, v76
	v_mul_f32_e32 v114, v106, v117
	v_mov_b32_e32 v106, v16
	v_mov_b32_e32 v107, v20
	v_pk_mul_f32 v[106:107], v[106:107], v[110:111]
	v_lshlrev_b32_e32 v184, 16, v112
	v_fma_f32 v81, v12, v81, v106
	v_lshlrev_b32_e32 v106, 16, v58
	v_mov_b32_e32 v117, v106
	v_pk_mul_f32 v[108:109], v[108:109], v[116:117]
	v_add_f32_e32 v81, v81, v107
	v_fma_f32 v108, v4, v97, v108
	v_add_f32_e32 v108, v108, v109
	v_lshlrev_b32_e32 v107, 16, v78
	v_mul_f32_e32 v116, v108, v119
	v_mov_b32_e32 v108, v4
	v_mov_b32_e32 v109, v8
	v_pk_mul_f32 v[108:109], v[108:109], v[106:107]
	v_and_b32_e32 v185, 0xffff0000, v112
	v_fma_f32 v97, v0, v97, v108
	v_and_b32_e32 v108, 0xffff0000, v56
	v_mov_b32_e32 v119, v108
	v_lshlrev_b32_e32 v186, 16, v113
	v_and_b32_e32 v187, 0xffff0000, v113
	v_pk_mul_f32 v[112:113], v[160:161], v[118:119]
	v_add_f32_e32 v97, v97, v109
	v_fma_f32 v56, v17, v99, v112
	v_and_b32_e32 v109, 0xffff0000, v76
	v_add_f32_e32 v56, v56, v113
	v_mov_b32_e32 v112, v17
	v_mov_b32_e32 v113, v21
	v_pk_mul_f32 v[112:113], v[112:113], v[108:109]
	v_mul_f32_e32 v56, v56, v155
	v_fma_f32 v76, v13, v99, v112
	v_and_b32_e32 v112, 0xffff0000, v58
	v_mov_b32_e32 v155, v112
	v_cvt_pk_bf16_f32 v56, v114, v56
	v_pk_mul_f32 v[114:115], v[162:163], v[154:155]
	v_add_f32_e32 v76, v76, v113
	v_fma_f32 v58, v5, v103, v114
	v_and_b32_e32 v113, 0xffff0000, v78
	v_add_f32_e32 v58, v58, v115
	v_mov_b32_e32 v114, v5
	v_mov_b32_e32 v115, v9
	v_pk_mul_f32 v[114:115], v[114:115], v[112:113]
	v_mul_f32_e32 v118, v76, v181
	v_fma_f32 v76, v1, v103, v114
	v_lshlrev_b32_e32 v114, 16, v57
	v_mul_f32_e32 v58, v58, v157
	v_mov_b32_e32 v157, v114
	v_cvt_pk_bf16_f32 v58, v116, v58
	v_add_f32_e32 v76, v76, v115
	v_pk_mul_f32 v[116:117], v[164:165], v[156:157]
	v_mul_f32_e32 v119, v76, v185
	v_fma_f32 v76, v18, v172, v116
	v_lshlrev_b32_e32 v115, 16, v77
	v_add_f32_e32 v76, v76, v117
	v_mov_b32_e32 v116, v18
	v_mov_b32_e32 v117, v22
	v_pk_mul_f32 v[116:117], v[116:117], v[114:115]
	v_mul_f32_e32 v78, v76, v176
	v_fma_f32 v76, v14, v172, v116
	v_lshlrev_b32_e32 v116, 16, v59
	v_mov_b32_e32 v103, v116
	v_add_f32_e32 v76, v76, v117
	v_pk_mul_f32 v[102:103], v[166:167], v[102:103]
	v_mul_f32_e32 v154, v76, v182
	v_fma_f32 v76, v6, v173, v102
	v_lshlrev_b32_e32 v117, 16, v79
	v_add_f32_e32 v76, v76, v103
	v_mov_b32_e32 v102, v6
	v_mov_b32_e32 v103, v10
	v_pk_mul_f32 v[102:103], v[102:103], v[116:117]
	v_mul_f32_e32 v155, v76, v178
	v_fma_f32 v76, v2, v173, v102
	v_ashrrev_i32_e32 v25, 31, v24
	v_add_f32_e32 v76, v76, v103
	v_lshlrev_b64 v[82:83], 11, v[24:25]
	v_mul_f32_e32 v102, v76, v186
	v_and_b32_e32 v76, 0xffff0000, v57
	v_or_b32_e32 v24, v82, v105
	v_mov_b32_e32 v25, v83
	v_mov_b32_e32 v168, v15
	v_mov_b32_e32 v169, v23
	v_mov_b32_e32 v99, v76
	v_lshl_add_u64 v[26:27], s[74:75], 0, v[24:25]
	v_lshl_add_u64 v[24:25], s[76:77], 0, v[24:25]
	v_pk_mul_f32 v[98:99], v[168:169], v[98:99]
	global_load_dwordx4 v[28:31], v[26:27], off nt
	s_nop 0
	global_load_dwordx4 v[24:27], v[24:25], off
	v_fma_f32 v57, v19, v174, v98
	v_and_b32_e32 v77, 0xffff0000, v77
	v_add_f32_e32 v57, v57, v99
	v_mov_b32_e32 v98, v19
	v_mov_b32_e32 v99, v23
	v_mul_f32_e32 v57, v57, v177
	v_pk_mul_f32 v[98:99], v[98:99], v[76:77]
	v_cvt_pk_bf16_f32 v57, v78, v57
	v_fma_f32 v78, v15, v174, v98
	v_add_f32_e32 v78, v78, v99
	v_mul_f32_e32 v98, v78, v183
	v_and_b32_e32 v78, 0xffff0000, v59
	v_mov_b32_e32 v170, v3
	v_mov_b32_e32 v171, v11
	v_mul_f32_e32 v81, v81, v180
	v_mul_f32_e32 v180, v97, v184
	v_mov_b32_e32 v97, v78
	v_pk_mul_f32 v[96:97], v[170:171], v[96:97]
	v_and_b32_e32 v79, 0xffff0000, v79
	v_fma_f32 v59, v7, v175, v96
	v_add_f32_e32 v59, v59, v97
	v_mul_f32_e32 v59, v59, v179
	v_cvt_pk_bf16_f32 v59, v155, v59
	global_store_dwordx4 v[100:101], v[56:59], off
	v_lshl_add_u64 v[94:95], v[132:133], 0, v[94:95]
	v_mov_b32_e32 v99, v112
	v_mov_b32_e32 v56, v7
	v_mov_b32_e32 v57, v11
	v_pk_mul_f32 v[56:57], v[56:57], v[78:79]
	v_cvt_pk_bf16_f32 v58, v180, v119
	v_fma_f32 v56, v3, v175, v56
	v_add_f32_e32 v56, v56, v57
	v_mul_f32_e32 v59, v56, v187
	v_cvt_pk_bf16_f32 v56, v81, v118
	v_cvt_pk_bf16_f32 v57, v154, v98
	v_cvt_pk_bf16_f32 v59, v102, v59
	global_store_dwordx4 v[94:95], v[56:59], off
	v_mov_b32_e32 v112, v107
	s_waitcnt vmcnt(13)
	v_lshlrev_b32_e32 v94, 16, v72
	v_mov_b32_e32 v59, v108
	v_mov_b32_e32 v108, v111
	v_mov_b32_e32 v58, v110
	v_pk_mul_f32 v[96:97], v[16:17], v[108:109]
	v_and_b32_e32 v95, 0xffff0000, v72
	v_pk_fma_f32 v[58:59], v[12:13], v[58:59], v[96:97]
	v_mov_b32_e32 v98, v106
	v_pk_mul_f32 v[100:101], v[4:5], v[112:113]
	s_waitcnt vmcnt(12)
	v_lshlrev_b32_e32 v56, 16, v68
	v_and_b32_e32 v57, 0xffff0000, v68
	v_pk_fma_f32 v[58:59], v[20:21], v[94:95], v[58:59]
	v_lshlrev_b32_e32 v96, 16, v74
	v_and_b32_e32 v97, 0xffff0000, v74
	v_pk_fma_f32 v[98:99], v[0:1], v[98:99], v[100:101]
	v_pk_mul_f32 v[56:57], v[58:59], v[56:57]
	v_lshlrev_b32_e32 v58, 16, v70
	v_and_b32_e32 v59, 0xffff0000, v70
	v_pk_fma_f32 v[98:99], v[8:9], v[96:97], v[98:99]
	v_lshlrev_b32_e32 v72, 16, v73
	v_pk_mul_f32 v[58:59], v[98:99], v[58:59]
	v_mov_b32_e32 v99, v76
	v_mov_b32_e32 v76, v115
	v_mov_b32_e32 v98, v114
	v_pk_mul_f32 v[100:101], v[18:19], v[76:77]
	v_and_b32_e32 v73, 0xffff0000, v73
	v_pk_fma_f32 v[98:99], v[14:15], v[98:99], v[100:101]
	v_lshlrev_b32_e32 v68, 16, v69
	v_and_b32_e32 v69, 0xffff0000, v69
	v_pk_fma_f32 v[98:99], v[22:23], v[72:73], v[98:99]
	v_lshlrev_b32_e32 v74, 16, v75
	v_pk_mul_f32 v[68:69], v[98:99], v[68:69]
	v_mov_b32_e32 v99, v78
	v_mov_b32_e32 v78, v117
	v_mov_b32_e32 v98, v116
	v_pk_mul_f32 v[100:101], v[6:7], v[78:79]
	v_and_b32_e32 v75, 0xffff0000, v75
	v_pk_fma_f32 v[98:99], v[2:3], v[98:99], v[100:101]
	v_lshlrev_b32_e32 v70, 16, v71
	v_and_b32_e32 v71, 0xffff0000, v71
	v_pk_fma_f32 v[98:99], v[10:11], v[74:75], v[98:99]
	v_cvt_pk_bf16_f32 v56, v56, v57
	v_pk_mul_f32 v[70:71], v[98:99], v[70:71]
	v_cvt_pk_bf16_f32 v57, v68, v69
	v_cvt_pk_bf16_f32 v58, v58, v59
	v_cvt_pk_bf16_f32 v59, v70, v71
	v_lshl_add_u64 v[68:69], v[132:133], 0, v[92:93]
	global_store_dwordx4 v[68:69], v[56:59], off
	s_waitcnt vmcnt(12)
	v_lshlrev_b32_e32 v68, 16, v64
	v_and_b32_e32 v69, 0xffff0000, v64
	v_pk_mul_f32 v[58:59], v[16:17], v[94:95]
	v_pk_mul_f32 v[92:93], v[4:5], v[96:97]
	v_pk_fma_f32 v[58:59], v[12:13], v[108:109], v[58:59]
	s_waitcnt vmcnt(11)
	v_lshlrev_b32_e32 v56, 16, v60
	v_and_b32_e32 v57, 0xffff0000, v60
	v_pk_fma_f32 v[58:59], v[20:21], v[68:69], v[58:59]
	v_lshlrev_b32_e32 v70, 16, v66
	v_and_b32_e32 v71, 0xffff0000, v66
	v_pk_fma_f32 v[92:93], v[0:1], v[112:113], v[92:93]
	v_pk_mul_f32 v[56:57], v[58:59], v[56:57]
	v_lshlrev_b32_e32 v58, 16, v62
	v_and_b32_e32 v59, 0xffff0000, v62
	v_pk_fma_f32 v[92:93], v[8:9], v[70:71], v[92:93]
	v_lshlrev_b32_e32 v64, 16, v65
	v_pk_mul_f32 v[58:59], v[92:93], v[58:59]
	v_pk_mul_f32 v[92:93], v[18:19], v[72:73]
	v_and_b32_e32 v65, 0xffff0000, v65
	v_pk_fma_f32 v[76:77], v[14:15], v[76:77], v[92:93]
	v_lshlrev_b32_e32 v60, 16, v61
	v_and_b32_e32 v61, 0xffff0000, v61
	v_pk_fma_f32 v[76:77], v[22:23], v[64:65], v[76:77]
	v_lshlrev_b32_e32 v66, 16, v67
	v_pk_mul_f32 v[60:61], v[76:77], v[60:61]
	v_pk_mul_f32 v[76:77], v[6:7], v[74:75]
	v_and_b32_e32 v67, 0xffff0000, v67
	v_pk_fma_f32 v[76:77], v[2:3], v[78:79], v[76:77]
	v_lshlrev_b32_e32 v62, 16, v63
	v_and_b32_e32 v63, 0xffff0000, v63
	v_pk_fma_f32 v[76:77], v[10:11], v[66:67], v[76:77]
	v_cvt_pk_bf16_f32 v56, v56, v57
	v_pk_mul_f32 v[62:63], v[76:77], v[62:63]
	v_cvt_pk_bf16_f32 v57, v60, v61
	v_cvt_pk_bf16_f32 v58, v58, v59
	v_cvt_pk_bf16_f32 v59, v62, v63
	v_lshl_add_u64 v[60:61], v[132:133], 0, v[90:91]
	global_store_dwordx4 v[60:61], v[56:59], off
	v_pk_mul_f32 v[60:61], v[16:17], v[68:69]
	v_pk_mul_f32 v[76:77], v[4:5], v[70:71]
	s_waitcnt vmcnt(11)
	v_lshlrev_b32_e32 v56, 16, v52
	v_and_b32_e32 v57, 0xffff0000, v52
	v_pk_fma_f32 v[60:61], v[12:13], v[94:95], v[60:61]
	s_waitcnt vmcnt(10)
	v_lshlrev_b32_e32 v58, 16, v48
	v_and_b32_e32 v59, 0xffff0000, v48
	v_pk_fma_f32 v[60:61], v[20:21], v[56:57], v[60:61]
	v_pk_fma_f32 v[76:77], v[0:1], v[96:97], v[76:77]
	v_pk_mul_f32 v[58:59], v[60:61], v[58:59]
	v_lshlrev_b32_e32 v60, 16, v54
	v_and_b32_e32 v61, 0xffff0000, v54
	v_lshlrev_b32_e32 v62, 16, v50
	v_and_b32_e32 v63, 0xffff0000, v50
	v_pk_fma_f32 v[76:77], v[8:9], v[60:61], v[76:77]
	v_lshlrev_b32_e32 v52, 16, v53
	v_pk_mul_f32 v[62:63], v[76:77], v[62:63]
	v_pk_mul_f32 v[76:77], v[18:19], v[64:65]
	v_and_b32_e32 v53, 0xffff0000, v53
	v_pk_fma_f32 v[72:73], v[14:15], v[72:73], v[76:77]
	v_lshlrev_b32_e32 v48, 16, v49
	v_and_b32_e32 v49, 0xffff0000, v49
	v_pk_fma_f32 v[72:73], v[22:23], v[52:53], v[72:73]
	v_lshlrev_b32_e32 v54, 16, v55
	v_pk_mul_f32 v[72:73], v[72:73], v[48:49]
	v_lshlrev_b32_e32 v48, 16, v51
	v_and_b32_e32 v49, 0xffff0000, v51
	v_pk_mul_f32 v[50:51], v[6:7], v[66:67]
	v_and_b32_e32 v55, 0xffff0000, v55
	v_pk_fma_f32 v[50:51], v[2:3], v[74:75], v[50:51]
	s_waitcnt vmcnt(7)
	v_lshlrev_b32_e32 v78, 16, v36
	v_pk_fma_f32 v[50:51], v[10:11], v[54:55], v[50:51]
	v_and_b32_e32 v79, 0xffff0000, v36
	v_pk_mul_f32 v[74:75], v[50:51], v[48:49]
	v_cvt_pk_bf16_f32 v48, v58, v59
	v_cvt_pk_bf16_f32 v49, v72, v73
	v_cvt_pk_bf16_f32 v50, v62, v63
	v_cvt_pk_bf16_f32 v51, v74, v75
	v_lshl_add_u64 v[58:59], v[132:133], 0, v[88:89]
	global_store_dwordx4 v[58:59], v[48:51], off
	v_pk_mul_f32 v[58:59], v[16:17], v[56:57]
	v_lshlrev_b32_e32 v62, 16, v42
	v_lshlrev_b32_e32 v48, 16, v44
	v_and_b32_e32 v49, 0xffff0000, v44
	v_pk_fma_f32 v[58:59], v[12:13], v[68:69], v[58:59]
	v_lshlrev_b32_e32 v50, 16, v40
	v_and_b32_e32 v51, 0xffff0000, v40
	v_pk_fma_f32 v[58:59], v[20:21], v[48:49], v[58:59]
	v_pk_mul_f32 v[68:69], v[4:5], v[60:61]
	v_pk_mul_f32 v[50:51], v[58:59], v[50:51]
	v_lshlrev_b32_e32 v58, 16, v46
	v_and_b32_e32 v59, 0xffff0000, v46
	v_pk_fma_f32 v[68:69], v[0:1], v[70:71], v[68:69]
	v_and_b32_e32 v63, 0xffff0000, v42
	v_pk_fma_f32 v[68:69], v[8:9], v[58:59], v[68:69]
	v_lshlrev_b32_e32 v44, 16, v45
	v_pk_mul_f32 v[62:63], v[68:69], v[62:63]
	v_pk_mul_f32 v[68:69], v[18:19], v[52:53]
	v_and_b32_e32 v45, 0xffff0000, v45
	v_pk_fma_f32 v[64:65], v[14:15], v[64:65], v[68:69]
	v_lshlrev_b32_e32 v40, 16, v41
	v_and_b32_e32 v41, 0xffff0000, v41
	v_pk_fma_f32 v[64:65], v[22:23], v[44:45], v[64:65]
	v_lshlrev_b32_e32 v46, 16, v47
	v_pk_mul_f32 v[64:65], v[64:65], v[40:41]
	v_lshlrev_b32_e32 v40, 16, v43
	v_and_b32_e32 v41, 0xffff0000, v43
	v_pk_mul_f32 v[42:43], v[6:7], v[54:55]
	v_and_b32_e32 v47, 0xffff0000, v47
	v_pk_fma_f32 v[42:43], v[2:3], v[66:67], v[42:43]
	v_lshlrev_b32_e32 v106, 16, v37
	v_pk_fma_f32 v[42:43], v[10:11], v[46:47], v[42:43]
	v_and_b32_e32 v107, 0xffff0000, v37
	v_pk_mul_f32 v[66:67], v[42:43], v[40:41]
	v_cvt_pk_bf16_f32 v40, v50, v51
	v_cvt_pk_bf16_f32 v41, v64, v65
	v_cvt_pk_bf16_f32 v42, v62, v63
	v_cvt_pk_bf16_f32 v43, v66, v67
	v_lshl_add_u64 v[50:51], v[132:133], 0, v[86:87]
	global_store_dwordx4 v[50:51], v[40:43], off
	v_pk_mul_f32 v[36:37], v[18:19], v[44:45]
	v_pk_mul_f32 v[50:51], v[4:5], v[58:59]
	v_pk_mul_f32 v[42:43], v[16:17], v[48:49]
	v_pk_fma_f32 v[36:37], v[14:15], v[52:53], v[36:37]
	v_pk_fma_f32 v[42:43], v[12:13], v[56:57], v[42:43]
	s_waitcnt vmcnt(8)
	v_lshlrev_b32_e32 v40, 16, v32
	v_and_b32_e32 v41, 0xffff0000, v32
	v_pk_fma_f32 v[42:43], v[20:21], v[78:79], v[42:43]
	v_lshlrev_b32_e32 v32, 16, v33
	v_and_b32_e32 v33, 0xffff0000, v33
	v_pk_fma_f32 v[36:37], v[22:23], v[106:107], v[36:37]
	v_pk_mul_f32 v[40:41], v[42:43], v[40:41]
	v_lshlrev_b32_e32 v42, 16, v34
	v_and_b32_e32 v43, 0xffff0000, v34
	v_pk_mul_f32 v[36:37], v[36:37], v[32:33]
	v_lshlrev_b32_e32 v32, 16, v35
	v_and_b32_e32 v33, 0xffff0000, v35
	v_pk_mul_f32 v[34:35], v[6:7], v[46:47]
	v_lshlrev_b32_e32 v102, 16, v38
	v_and_b32_e32 v103, 0xffff0000, v38
	v_pk_fma_f32 v[50:51], v[0:1], v[60:61], v[50:51]
	v_lshlrev_b32_e32 v108, 16, v39
	v_and_b32_e32 v109, 0xffff0000, v39
	v_pk_fma_f32 v[34:35], v[2:3], v[54:55], v[34:35]
	v_pk_fma_f32 v[50:51], v[8:9], v[102:103], v[50:51]
	v_pk_fma_f32 v[34:35], v[10:11], v[108:109], v[34:35]
	v_pk_mul_f32 v[42:43], v[50:51], v[42:43]
	v_pk_mul_f32 v[38:39], v[34:35], v[32:33]
	v_cvt_pk_bf16_f32 v32, v40, v41
	v_cvt_pk_bf16_f32 v33, v36, v37
	v_cvt_pk_bf16_f32 v34, v42, v43
	v_cvt_pk_bf16_f32 v35, v38, v39
	v_lshl_add_u64 v[36:37], v[132:133], 0, v[84:85]
	global_store_dwordx4 v[36:37], v[32:35], off
	s_waitcnt vmcnt(8)
	v_lshlrev_b32_e32 v110, 16, v28
	v_and_b32_e32 v111, 0xffff0000, v28
	v_pk_mul_f32 v[34:35], v[16:17], v[78:79]
	v_lshlrev_b32_e32 v114, 16, v29
	v_and_b32_e32 v115, 0xffff0000, v29
	v_pk_mul_f32 v[28:29], v[18:19], v[106:107]
	v_pk_fma_f32 v[34:35], v[12:13], v[48:49], v[34:35]
	v_pk_fma_f32 v[28:29], v[14:15], v[44:45], v[28:29]
	s_waitcnt vmcnt(7)
	v_lshlrev_b32_e32 v32, 16, v24
	v_and_b32_e32 v33, 0xffff0000, v24
	v_pk_fma_f32 v[34:35], v[20:21], v[110:111], v[34:35]
	v_lshlrev_b32_e32 v24, 16, v25
	v_and_b32_e32 v25, 0xffff0000, v25
	v_pk_fma_f32 v[28:29], v[22:23], v[114:115], v[28:29]
	v_pk_mul_f32 v[32:33], v[34:35], v[32:33]
	v_lshlrev_b32_e32 v34, 16, v26
	v_and_b32_e32 v35, 0xffff0000, v26
	v_pk_mul_f32 v[36:37], v[4:5], v[102:103]
	v_pk_mul_f32 v[28:29], v[28:29], v[24:25]
	v_lshlrev_b32_e32 v24, 16, v27
	v_and_b32_e32 v25, 0xffff0000, v27
	v_pk_mul_f32 v[26:27], v[6:7], v[108:109]
	v_lshlrev_b32_e32 v112, 16, v30
	v_and_b32_e32 v113, 0xffff0000, v30
	v_pk_fma_f32 v[36:37], v[0:1], v[58:59], v[36:37]
	v_lshlrev_b32_e32 v116, 16, v31
	v_and_b32_e32 v117, 0xffff0000, v31
	v_pk_fma_f32 v[26:27], v[2:3], v[46:47], v[26:27]
	v_pk_fma_f32 v[36:37], v[8:9], v[112:113], v[36:37]
	v_pk_fma_f32 v[26:27], v[10:11], v[116:117], v[26:27]
	v_pk_mul_f32 v[34:35], v[36:37], v[34:35]
	v_pk_mul_f32 v[30:31], v[26:27], v[24:25]
	v_cvt_pk_bf16_f32 v24, v32, v33
	v_cvt_pk_bf16_f32 v25, v28, v29
	v_cvt_pk_bf16_f32 v26, v34, v35
	v_cvt_pk_bf16_f32 v27, v30, v31
	v_lshl_add_u64 v[28:29], v[132:133], 0, v[82:83]
	global_store_dwordx4 v[28:29], v[24:27], off
	v_pk_mul_f32 v[164:165], v[16:17], v[110:111]
	v_pk_mul_f32 v[166:167], v[4:5], v[112:113]
	v_add_u32_e32 v24, 8, v80
	v_ashrrev_i32_e32 v25, 31, v24
	v_lshlrev_b64 v[118:119], 11, v[24:25]
	v_or_b32_e32 v24, v118, v105
	v_mov_b32_e32 v25, v119
	v_lshl_add_u64 v[26:27], s[74:75], 0, v[24:25]
	global_load_dwordx4 v[74:77], v[26:27], off nt
	v_lshl_add_u64 v[24:25], s[76:77], 0, v[24:25]
	global_load_dwordx4 v[82:85], v[24:25], off
	v_add_u32_e32 v24, 9, v80
	v_ashrrev_i32_e32 v25, 31, v24
	v_lshlrev_b64 v[154:155], 11, v[24:25]
	v_or_b32_e32 v24, v154, v105
	v_mov_b32_e32 v25, v155
	v_lshl_add_u64 v[26:27], s[74:75], 0, v[24:25]
	v_lshl_add_u64 v[24:25], s[76:77], 0, v[24:25]
	global_load_dwordx4 v[86:89], v[26:27], off nt
	global_load_dwordx4 v[90:93], v[24:25], off
	v_add_u32_e32 v24, 10, v80
	v_ashrrev_i32_e32 v25, 31, v24
	v_lshlrev_b64 v[156:157], 11, v[24:25]
	v_or_b32_e32 v24, v156, v105
	v_mov_b32_e32 v25, v157
	v_lshl_add_u64 v[26:27], s[74:75], 0, v[24:25]
	v_lshl_add_u64 v[24:25], s[76:77], 0, v[24:25]
	global_load_dwordx4 v[94:97], v[26:27], off nt
	global_load_dwordx4 v[98:101], v[24:25], off
	v_add_u32_e32 v24, 11, v80
	v_ashrrev_i32_e32 v25, 31, v24
	v_lshlrev_b64 v[72:73], 11, v[24:25]
	v_or_b32_e32 v24, v72, v105
	v_mov_b32_e32 v25, v73
	v_lshl_add_u64 v[26:27], s[74:75], 0, v[24:25]
	v_lshl_add_u64 v[24:25], s[76:77], 0, v[24:25]
	global_load_dwordx4 v[60:63], v[26:27], off nt
	global_load_dwordx4 v[56:59], v[24:25], off
	v_add_u32_e32 v24, 12, v80
	v_ashrrev_i32_e32 v25, 31, v24
	v_lshlrev_b64 v[70:71], 11, v[24:25]
	v_or_b32_e32 v24, v70, v105
	v_mov_b32_e32 v25, v71
	v_lshl_add_u64 v[26:27], s[74:75], 0, v[24:25]
	v_lshl_add_u64 v[24:25], s[76:77], 0, v[24:25]
	global_load_dwordx4 v[52:55], v[26:27], off nt
	global_load_dwordx4 v[48:51], v[24:25], off
	v_add_u32_e32 v24, 13, v80
	v_ashrrev_i32_e32 v25, 31, v24
	v_lshlrev_b64 v[68:69], 11, v[24:25]
	v_or_b32_e32 v24, v68, v105
	v_mov_b32_e32 v25, v69
	v_lshl_add_u64 v[26:27], s[74:75], 0, v[24:25]
	v_lshl_add_u64 v[24:25], s[76:77], 0, v[24:25]
	global_load_dwordx4 v[44:47], v[26:27], off nt
	global_load_dwordx4 v[40:43], v[24:25], off
	v_add_u32_e32 v24, 14, v80
	v_ashrrev_i32_e32 v25, 31, v24
	v_lshlrev_b64 v[66:67], 11, v[24:25]
	v_or_b32_e32 v24, v66, v105
	v_mov_b32_e32 v25, v67
	v_lshl_add_u64 v[26:27], s[74:75], 0, v[24:25]
	v_lshl_add_u64 v[24:25], s[76:77], 0, v[24:25]
	global_load_dwordx4 v[36:39], v[26:27], off nt
	global_load_dwordx4 v[32:35], v[24:25], off
	v_pk_fma_f32 v[78:79], v[12:13], v[78:79], v[164:165]
	v_add_u32_e32 v24, 15, v80
	v_pk_fma_f32 v[102:103], v[0:1], v[102:103], v[166:167]
	v_ashrrev_i32_e32 v25, 31, v24
	v_lshlrev_b64 v[64:65], 11, v[24:25]
	v_or_b32_e32 v24, v64, v105
	v_mov_b32_e32 v25, v65
	v_lshl_add_u64 v[26:27], s[74:75], 0, v[24:25]
	v_lshl_add_u64 v[24:25], s[76:77], 0, v[24:25]
	global_load_dwordx4 v[28:31], v[26:27], off nt
	s_nop 0
	global_load_dwordx4 v[24:27], v[24:25], off
	v_lshl_add_u64 v[72:73], v[132:133], 0, v[72:73]
	s_waitcnt vmcnt(15)
	v_lshlrev_b32_e32 v160, 16, v74
	v_and_b32_e32 v161, 0xffff0000, v74
	s_waitcnt vmcnt(14)
	v_lshlrev_b32_e32 v162, 16, v82
	v_and_b32_e32 v163, 0xffff0000, v82
	v_pk_fma_f32 v[78:79], v[20:21], v[160:161], v[78:79]
	v_lshlrev_b32_e32 v164, 16, v84
	v_pk_mul_f32 v[78:79], v[78:79], v[162:163]
	v_lshlrev_b32_e32 v162, 16, v76
	v_and_b32_e32 v163, 0xffff0000, v76
	v_and_b32_e32 v165, 0xffff0000, v84
	v_pk_fma_f32 v[102:103], v[8:9], v[162:163], v[102:103]
	v_lshlrev_b32_e32 v74, 16, v83
	v_pk_mul_f32 v[102:103], v[102:103], v[164:165]
	v_lshlrev_b32_e32 v164, 16, v75
	v_and_b32_e32 v165, 0xffff0000, v75
	v_and_b32_e32 v75, 0xffff0000, v83
	v_pk_mul_f32 v[82:83], v[18:19], v[114:115]
	s_nop 0
	v_pk_fma_f32 v[82:83], v[14:15], v[106:107], v[82:83]
	v_lshlrev_b32_e32 v106, 16, v77
	v_and_b32_e32 v107, 0xffff0000, v77
	v_pk_mul_f32 v[76:77], v[6:7], v[116:117]
	v_pk_fma_f32 v[82:83], v[22:23], v[164:165], v[82:83]
	v_pk_fma_f32 v[76:77], v[2:3], v[108:109], v[76:77]
	v_pk_mul_f32 v[82:83], v[82:83], v[74:75]
	v_lshlrev_b32_e32 v74, 16, v85
	v_and_b32_e32 v75, 0xffff0000, v85
	v_pk_fma_f32 v[76:77], v[10:11], v[106:107], v[76:77]
	s_nop 0
	v_pk_mul_f32 v[84:85], v[76:77], v[74:75]
	v_cvt_pk_bf16_f32 v74, v78, v79
	v_cvt_pk_bf16_f32 v75, v82, v83
	v_cvt_pk_bf16_f32 v76, v102, v103
	v_cvt_pk_bf16_f32 v77, v84, v85
	v_lshl_add_u64 v[78:79], v[132:133], 0, v[118:119]
	global_store_dwordx4 v[78:79], v[74:77], off
	s_waitcnt vmcnt(14)
	v_lshlrev_b32_e32 v78, 16, v86
	v_and_b32_e32 v79, 0xffff0000, v86
	v_pk_mul_f32 v[76:77], v[16:17], v[160:161]
	v_pk_mul_f32 v[84:85], v[4:5], v[162:163]
	v_pk_fma_f32 v[76:77], v[12:13], v[110:111], v[76:77]
	s_waitcnt vmcnt(13)
	v_lshlrev_b32_e32 v74, 16, v90
	v_and_b32_e32 v75, 0xffff0000, v90
	v_pk_fma_f32 v[76:77], v[20:21], v[78:79], v[76:77]
	v_lshlrev_b32_e32 v82, 16, v88
	v_and_b32_e32 v83, 0xffff0000, v88
	v_pk_fma_f32 v[84:85], v[0:1], v[112:113], v[84:85]
	v_pk_mul_f32 v[74:75], v[76:77], v[74:75]
	v_lshlrev_b32_e32 v76, 16, v92
	v_and_b32_e32 v77, 0xffff0000, v92
	v_pk_fma_f32 v[84:85], v[8:9], v[82:83], v[84:85]
	v_lshlrev_b32_e32 v86, 16, v91
	v_pk_mul_f32 v[76:77], v[84:85], v[76:77]
	v_lshlrev_b32_e32 v84, 16, v87
	v_and_b32_e32 v85, 0xffff0000, v87
	v_and_b32_e32 v87, 0xffff0000, v91
	v_pk_mul_f32 v[90:91], v[18:19], v[164:165]
	v_lshlrev_b32_e32 v88, 16, v89
	v_pk_fma_f32 v[90:91], v[14:15], v[114:115], v[90:91]
	v_and_b32_e32 v89, 0xffff0000, v89
	v_pk_fma_f32 v[90:91], v[22:23], v[84:85], v[90:91]
	v_cvt_pk_bf16_f32 v74, v74, v75
	v_pk_mul_f32 v[86:87], v[90:91], v[86:87]
	v_lshlrev_b32_e32 v90, 16, v93
	v_and_b32_e32 v91, 0xffff0000, v93
	v_pk_mul_f32 v[92:93], v[6:7], v[106:107]
	v_cvt_pk_bf16_f32 v75, v86, v87
	v_pk_fma_f32 v[92:93], v[2:3], v[116:117], v[92:93]
	v_cvt_pk_bf16_f32 v76, v76, v77
	v_pk_fma_f32 v[92:93], v[10:11], v[88:89], v[92:93]
	v_lshl_add_u64 v[86:87], v[132:133], 0, v[154:155]
	v_pk_mul_f32 v[90:91], v[92:93], v[90:91]
	v_pk_mul_f32 v[92:93], v[4:5], v[82:83]
	v_cvt_pk_bf16_f32 v77, v90, v91
	global_store_dwordx4 v[86:87], v[74:77], off
	s_waitcnt vmcnt(13)
	v_lshlrev_b32_e32 v86, 16, v94
	v_and_b32_e32 v87, 0xffff0000, v94
	v_pk_mul_f32 v[76:77], v[16:17], v[78:79]
	s_waitcnt vmcnt(12)
	v_lshlrev_b32_e32 v74, 16, v98
	v_pk_fma_f32 v[76:77], v[12:13], v[160:161], v[76:77]
	v_and_b32_e32 v75, 0xffff0000, v98
	v_pk_fma_f32 v[76:77], v[20:21], v[86:87], v[76:77]
	v_lshlrev_b32_e32 v90, 16, v96
	v_and_b32_e32 v91, 0xffff0000, v96
	v_pk_fma_f32 v[92:93], v[0:1], v[162:163], v[92:93]
	v_pk_mul_f32 v[74:75], v[76:77], v[74:75]
	v_lshlrev_b32_e32 v76, 16, v100
	v_and_b32_e32 v77, 0xffff0000, v100
	v_pk_fma_f32 v[92:93], v[8:9], v[90:91], v[92:93]
	v_lshlrev_b32_e32 v94, 16, v99
	v_pk_mul_f32 v[76:77], v[92:93], v[76:77]
	v_lshlrev_b32_e32 v92, 16, v95
	v_and_b32_e32 v93, 0xffff0000, v95
	v_and_b32_e32 v95, 0xffff0000, v99
	v_pk_mul_f32 v[98:99], v[18:19], v[84:85]
	v_lshlrev_b32_e32 v96, 16, v97
	v_pk_fma_f32 v[98:99], v[14:15], v[164:165], v[98:99]
	v_and_b32_e32 v97, 0xffff0000, v97
	v_pk_fma_f32 v[98:99], v[22:23], v[92:93], v[98:99]
	v_cvt_pk_bf16_f32 v74, v74, v75
	v_pk_mul_f32 v[94:95], v[98:99], v[94:95]
	v_lshlrev_b32_e32 v98, 16, v101
	v_and_b32_e32 v99, 0xffff0000, v101
	v_pk_mul_f32 v[100:101], v[6:7], v[88:89]
	v_cvt_pk_bf16_f32 v75, v94, v95
	v_pk_fma_f32 v[100:101], v[2:3], v[106:107], v[100:101]
	v_cvt_pk_bf16_f32 v76, v76, v77
	v_pk_fma_f32 v[100:101], v[10:11], v[96:97], v[100:101]
	v_lshl_add_u64 v[94:95], v[132:133], 0, v[156:157]
	v_pk_mul_f32 v[98:99], v[100:101], v[98:99]
	s_nop 0
	v_cvt_pk_bf16_f32 v77, v98, v99
	global_store_dwordx4 v[94:95], v[74:77], off
	v_pk_mul_f32 v[94:95], v[16:17], v[86:87]
	v_pk_mul_f32 v[98:99], v[4:5], v[90:91]
	s_waitcnt vmcnt(12)
	v_lshlrev_b32_e32 v74, 16, v60
	v_and_b32_e32 v75, 0xffff0000, v60
	v_pk_fma_f32 v[78:79], v[12:13], v[78:79], v[94:95]
	s_waitcnt vmcnt(11)
	v_lshlrev_b32_e32 v76, 16, v56
	v_and_b32_e32 v77, 0xffff0000, v56
	v_pk_fma_f32 v[78:79], v[20:21], v[74:75], v[78:79]
	v_pk_fma_f32 v[82:83], v[0:1], v[82:83], v[98:99]
	v_pk_mul_f32 v[76:77], v[78:79], v[76:77]
	v_lshlrev_b32_e32 v78, 16, v62
	v_and_b32_e32 v79, 0xffff0000, v62
	v_lshlrev_b32_e32 v94, 16, v58
	v_and_b32_e32 v95, 0xffff0000, v58
	v_pk_fma_f32 v[82:83], v[8:9], v[78:79], v[82:83]
	v_lshlrev_b32_e32 v60, 16, v61
	v_pk_mul_f32 v[82:83], v[82:83], v[94:95]
	v_pk_mul_f32 v[94:95], v[18:19], v[92:93]
	v_and_b32_e32 v61, 0xffff0000, v61
	v_pk_fma_f32 v[84:85], v[14:15], v[84:85], v[94:95]
	v_lshlrev_b32_e32 v56, 16, v57
	v_and_b32_e32 v57, 0xffff0000, v57
	v_pk_fma_f32 v[84:85], v[22:23], v[60:61], v[84:85]
	v_lshlrev_b32_e32 v62, 16, v63
	v_pk_mul_f32 v[84:85], v[84:85], v[56:57]
	v_lshlrev_b32_e32 v56, 16, v59
	v_and_b32_e32 v57, 0xffff0000, v59
	v_pk_mul_f32 v[58:59], v[6:7], v[96:97]
	v_and_b32_e32 v63, 0xffff0000, v63
	v_pk_fma_f32 v[58:59], v[2:3], v[88:89], v[58:59]
	s_nop 0
	v_pk_fma_f32 v[58:59], v[10:11], v[62:63], v[58:59]
	s_nop 0
	v_pk_mul_f32 v[88:89], v[58:59], v[56:57]
	v_cvt_pk_bf16_f32 v56, v76, v77
	v_cvt_pk_bf16_f32 v57, v84, v85
	v_cvt_pk_bf16_f32 v58, v82, v83
	v_cvt_pk_bf16_f32 v59, v88, v89
	global_store_dwordx4 v[72:73], v[56:59], off
	v_pk_mul_f32 v[72:73], v[16:17], v[74:75]
	v_pk_mul_f32 v[82:83], v[4:5], v[78:79]
	s_waitcnt vmcnt(11)
	v_lshlrev_b32_e32 v56, 16, v52
	v_and_b32_e32 v57, 0xffff0000, v52
	v_pk_fma_f32 v[72:73], v[12:13], v[86:87], v[72:73]
	s_waitcnt vmcnt(10)
	v_lshlrev_b32_e32 v58, 16, v48
	v_and_b32_e32 v59, 0xffff0000, v48
	v_pk_fma_f32 v[72:73], v[20:21], v[56:57], v[72:73]
	v_pk_fma_f32 v[82:83], v[0:1], v[90:91], v[82:83]
	v_pk_mul_f32 v[58:59], v[72:73], v[58:59]
	v_lshlrev_b32_e32 v72, 16, v54
	v_and_b32_e32 v73, 0xffff0000, v54
	v_lshlrev_b32_e32 v76, 16, v50
	v_and_b32_e32 v77, 0xffff0000, v50
	v_pk_fma_f32 v[82:83], v[8:9], v[72:73], v[82:83]
	v_lshlrev_b32_e32 v52, 16, v53
	v_pk_mul_f32 v[76:77], v[82:83], v[76:77]
	v_pk_mul_f32 v[82:83], v[18:19], v[60:61]
	v_and_b32_e32 v53, 0xffff0000, v53
	v_pk_fma_f32 v[82:83], v[14:15], v[92:93], v[82:83]
	v_lshlrev_b32_e32 v48, 16, v49
	v_and_b32_e32 v49, 0xffff0000, v49
	v_pk_fma_f32 v[82:83], v[22:23], v[52:53], v[82:83]
	v_lshlrev_b32_e32 v54, 16, v55
	v_pk_mul_f32 v[82:83], v[82:83], v[48:49]
	v_lshlrev_b32_e32 v48, 16, v51
	v_and_b32_e32 v49, 0xffff0000, v51
	v_pk_mul_f32 v[50:51], v[6:7], v[62:63]
	v_and_b32_e32 v55, 0xffff0000, v55
	v_pk_fma_f32 v[50:51], v[2:3], v[96:97], v[50:51]
	s_nop 0
	v_pk_fma_f32 v[50:51], v[10:11], v[54:55], v[50:51]
	s_nop 0
	v_pk_mul_f32 v[84:85], v[50:51], v[48:49]
	v_cvt_pk_bf16_f32 v48, v58, v59
	v_cvt_pk_bf16_f32 v49, v82, v83
	v_cvt_pk_bf16_f32 v50, v76, v77
	v_cvt_pk_bf16_f32 v51, v84, v85
	v_lshl_add_u64 v[58:59], v[132:133], 0, v[70:71]
	global_store_dwordx4 v[58:59], v[48:51], off
	v_pk_mul_f32 v[58:59], v[16:17], v[56:57]
	s_waitcnt vmcnt(9)
	v_lshlrev_b32_e32 v70, 16, v42
	v_lshlrev_b32_e32 v48, 16, v44
	v_and_b32_e32 v49, 0xffff0000, v44
	v_pk_fma_f32 v[58:59], v[12:13], v[74:75], v[58:59]
	v_lshlrev_b32_e32 v50, 16, v40
	v_and_b32_e32 v51, 0xffff0000, v40
	v_pk_fma_f32 v[58:59], v[20:21], v[48:49], v[58:59]
	v_pk_mul_f32 v[74:75], v[4:5], v[72:73]
	v_pk_mul_f32 v[50:51], v[58:59], v[50:51]
	v_lshlrev_b32_e32 v58, 16, v46
	v_and_b32_e32 v59, 0xffff0000, v46
	v_pk_fma_f32 v[74:75], v[0:1], v[78:79], v[74:75]
	v_and_b32_e32 v71, 0xffff0000, v42
	v_pk_fma_f32 v[74:75], v[8:9], v[58:59], v[74:75]
	v_lshlrev_b32_e32 v40, 16, v41
	v_pk_mul_f32 v[70:71], v[74:75], v[70:71]
	v_lshlrev_b32_e32 v74, 16, v45
	v_and_b32_e32 v75, 0xffff0000, v45
	v_pk_mul_f32 v[44:45], v[18:19], v[52:53]
	v_and_b32_e32 v41, 0xffff0000, v41
	v_pk_fma_f32 v[44:45], v[14:15], v[60:61], v[44:45]
	v_lshlrev_b32_e32 v60, 16, v47
	v_pk_fma_f32 v[44:45], v[22:23], v[74:75], v[44:45]
	v_and_b32_e32 v61, 0xffff0000, v47
	v_pk_mul_f32 v[44:45], v[44:45], v[40:41]
	v_lshlrev_b32_e32 v40, 16, v43
	v_and_b32_e32 v41, 0xffff0000, v43
	v_pk_mul_f32 v[42:43], v[6:7], v[54:55]
	s_nop 0
	v_pk_fma_f32 v[42:43], v[2:3], v[62:63], v[42:43]
	s_nop 0
	v_pk_fma_f32 v[42:43], v[10:11], v[60:61], v[42:43]
	s_nop 0
	v_pk_mul_f32 v[46:47], v[42:43], v[40:41]
	v_cvt_pk_bf16_f32 v40, v50, v51
	v_cvt_pk_bf16_f32 v41, v44, v45
	v_cvt_pk_bf16_f32 v42, v70, v71
	v_cvt_pk_bf16_f32 v43, v46, v47
	v_lshl_add_u64 v[44:45], v[132:133], 0, v[68:69]
	global_store_dwordx4 v[44:45], v[40:43], off
	v_pk_mul_f32 v[44:45], v[16:17], v[48:49]
	v_pk_mul_f32 v[46:47], v[4:5], v[58:59]
	s_waitcnt vmcnt(9)
	v_lshlrev_b32_e32 v40, 16, v36
	v_and_b32_e32 v41, 0xffff0000, v36
	v_pk_fma_f32 v[44:45], v[12:13], v[56:57], v[44:45]
	s_waitcnt vmcnt(8)
	v_lshlrev_b32_e32 v42, 16, v32
	v_and_b32_e32 v43, 0xffff0000, v32
	v_pk_fma_f32 v[44:45], v[20:21], v[40:41], v[44:45]
	v_pk_fma_f32 v[46:47], v[0:1], v[72:73], v[46:47]
	v_pk_mul_f32 v[50:51], v[44:45], v[42:43]
	v_lshlrev_b32_e32 v44, 16, v38
	v_and_b32_e32 v45, 0xffff0000, v38
	v_lshlrev_b32_e32 v42, 16, v34
	v_and_b32_e32 v43, 0xffff0000, v34
	v_pk_fma_f32 v[46:47], v[8:9], v[44:45], v[46:47]
	v_lshlrev_b32_e32 v32, 16, v33
	v_pk_mul_f32 v[56:57], v[46:47], v[42:43]
	v_lshlrev_b32_e32 v42, 16, v37
	v_and_b32_e32 v43, 0xffff0000, v37
	v_pk_mul_f32 v[36:37], v[18:19], v[74:75]
	v_and_b32_e32 v33, 0xffff0000, v33
	v_pk_fma_f32 v[36:37], v[14:15], v[52:53], v[36:37]
	v_lshlrev_b32_e32 v46, 16, v39
	v_pk_fma_f32 v[36:37], v[22:23], v[42:43], v[36:37]
	v_and_b32_e32 v47, 0xffff0000, v39
	v_pk_mul_f32 v[36:37], v[36:37], v[32:33]
	v_lshlrev_b32_e32 v32, 16, v35
	v_and_b32_e32 v33, 0xffff0000, v35
	v_pk_mul_f32 v[34:35], v[6:7], v[60:61]
	v_pk_mul_f32 v[16:17], v[16:17], v[40:41]
	v_pk_fma_f32 v[34:35], v[2:3], v[54:55], v[34:35]
	v_pk_fma_f32 v[12:13], v[12:13], v[48:49], v[16:17]
	v_pk_fma_f32 v[34:35], v[10:11], v[46:47], v[34:35]
	v_pk_mul_f32 v[4:5], v[4:5], v[44:45]
	v_pk_mul_f32 v[38:39], v[34:35], v[32:33]
	v_cvt_pk_bf16_f32 v32, v50, v51
	v_cvt_pk_bf16_f32 v33, v36, v37
	v_cvt_pk_bf16_f32 v34, v56, v57
	v_cvt_pk_bf16_f32 v35, v38, v39
	v_lshl_add_u64 v[36:37], v[132:133], 0, v[66:67]
	global_store_dwordx4 v[36:37], v[32:35], off
	v_pk_fma_f32 v[0:1], v[0:1], v[58:59], v[4:5]
	v_pk_mul_f32 v[6:7], v[6:7], v[46:47]
	s_waitcnt vmcnt(8)
	v_lshlrev_b32_e32 v32, 16, v28
	v_and_b32_e32 v33, 0xffff0000, v28
	s_waitcnt vmcnt(7)
	v_lshlrev_b32_e32 v34, 16, v24
	v_and_b32_e32 v35, 0xffff0000, v24
	v_pk_fma_f32 v[12:13], v[20:21], v[32:33], v[12:13]
	v_lshlrev_b32_e32 v20, 16, v26
	v_pk_mul_f32 v[16:17], v[12:13], v[34:35]
	v_lshlrev_b32_e32 v12, 16, v30
	v_and_b32_e32 v13, 0xffff0000, v30
	v_pk_fma_f32 v[0:1], v[8:9], v[12:13], v[0:1]
	v_pk_mul_f32 v[8:9], v[18:19], v[42:43]
	v_and_b32_e32 v21, 0xffff0000, v26
	v_lshlrev_b32_e32 v34, 16, v29
	v_and_b32_e32 v35, 0xffff0000, v29
	v_pk_fma_f32 v[8:9], v[14:15], v[74:75], v[8:9]
	v_pk_mul_f32 v[4:5], v[0:1], v[20:21]
	v_lshlrev_b32_e32 v0, 16, v25
	v_and_b32_e32 v1, 0xffff0000, v25
	v_pk_fma_f32 v[8:9], v[22:23], v[34:35], v[8:9]
	v_lshlrev_b32_e32 v14, 16, v31
	v_and_b32_e32 v15, 0xffff0000, v31
	v_pk_fma_f32 v[2:3], v[2:3], v[60:61], v[6:7]
	v_pk_mul_f32 v[8:9], v[8:9], v[0:1]
	v_lshlrev_b32_e32 v0, 16, v27
	v_and_b32_e32 v1, 0xffff0000, v27
	v_pk_fma_f32 v[2:3], v[10:11], v[14:15], v[2:3]
	s_nop 0
	v_pk_mul_f32 v[6:7], v[2:3], v[0:1]
	v_cvt_pk_bf16_f32 v0, v16, v17
	v_cvt_pk_bf16_f32 v1, v8, v9
	v_cvt_pk_bf16_f32 v2, v4, v5
	v_cvt_pk_bf16_f32 v3, v6, v7
	v_lshl_add_u64 v[4:5], v[132:133], 0, v[64:65]
	global_store_dwordx4 v[4:5], v[0:3], off
	s_nop 1
	v_or_b32_e32 v0, 15, v104
	v_cndmask_b32_e32 v1, 31, v243, vcc
	v_cmp_eq_u32_e64 s[0:1], v0, v1
	s_and_saveexec_b64 s[10:11], s[0:1]
	s_cbranch_execz .LBB0_410
	v_ashrrev_i32_e32 v0, 11, v80
	v_mov_b32_e32 v1, s31
	v_mov_b32_e32 v2, s49
	v_cndmask_b32_e32 v0, v194, v0, vcc
	v_cndmask_b32_e32 v3, v1, v2, vcc
	v_mov_b32_e32 v1, s30
	v_mov_b32_e32 v2, s48
	v_cndmask_b32_e32 v2, v1, v2, vcc
	v_ashrrev_i32_e32 v1, 31, v0
	v_lshlrev_b64 v[0:1], 13, v[0:1]
	v_lshl_add_u64 v[0:1], v[2:3], 0, v[0:1]
	v_lshlrev_b32_e32 v194, 2, v120
	v_lshl_add_u64 v[0:1], v[0:1], 0, v[194:195]
	global_store_dwordx4 v[0:1], v[40:43], off
	global_store_dwordx4 v[0:1], v[44:47], off offset:16
	v_add_co_u32_e32 v0, vcc, 0x1000, v0
	s_nop 1
	v_addc_co_u32_e32 v1, vcc, 0, v1, vcc
	global_store_dwordx4 v[0:1], v[32:35], off
	global_store_dwordx4 v[0:1], v[12:15], off offset:16
	s_branch .LBB0_410
